# grid barrier: drop the unused per-XCC generation bump and its waits from the leader exit path
# speedup vs baseline: 1.0850x; 1.0022x over previous
.Lcgx_298:
	s_or_b64 exec, exec, s[6:7]
	s_mov_b64 s[6:7], exec
	v_mbcnt_lo_u32_b32 v0, s6, 0
	v_mbcnt_hi_u32_b32 v0, s7, v0
	v_cmp_eq_u32_e32 vcc, 0, v0
	s_and_saveexec_b64 s[10:11], vcc
	s_cbranch_execz .Lcgx_300
	s_bcnt1_i32_b64 s3, s[6:7]
	v_mov_b32_e32 v0, 0x2000
	v_mov_b32_e32 v1, s3
.Lcgx_300:
	s_or_b64 exec, exec, s[10:11]
.Lcgx_301:
	s_or_b64 exec, exec, s[4:5]
	s_waitcnt lgkmcnt(0)
	s_mov_b32 s100, 0
	s_mov_b64 s[4:5], s[0:1]
	s_mov_b64 s[8:9], s[0:1]
	s_mov_b32 s3, s33
	s_mov_b32 s40, s2
	s_barrier
	v_mov_b32_e32 v8, v154
	s_cmpk_lt_i32 s40, 0x2c0
	s_cselect_b64 s[10:11], -1, 0
	s_cmpk_gt_i32 s40, 0x2bf
	v_readfirstlane_b32 s12, v8
	s_cbranch_scc1 .LBB0_217
	s_ashr_i32 s6, s40, 31
	s_lshr_b32 s6, s6, 29
	s_add_i32 s6, s40, s6
	s_ashr_i32 s7, s6, 3
	s_and_b32 s6, s6, -8
	s_sub_i32 s6, s40, s6
	s_cmp_lt_i32 s6, 0
	s_movk_i32 s13, 0x59
	s_cselect_b32 s13, s13, 0x58
	s_mul_i32 s6, s13, s6
	s_add_i32 s6, s6, s7
	s_mul_hi_i32 s7, s6, 0x2e8ba2e9
	s_lshr_b32 s13, s7, 31
	s_ashr_i32 s7, s7, 4
	s_add_i32 s7, s7, s13
	s_lshl_b32 s13, s7, 3
	s_mulk_i32 s7, 0x58
	s_sub_i32 s6, s6, s7
	s_bfe_i32 s7, s6, 0x80000
	s_bfe_u32 s7, s7, 0x3000c
	s_add_i32 s7, s6, s7
	s_bfe_i32 s14, s7, 0x80000
	s_and_b32 s7, s7, 0xf8
	s_sub_i32 s6, s6, s7
	s_sext_i32_i16 s14, s14
	s_sext_i32_i8 s6, s6
	s_add_i32 s30, s13, s6
	s_ashr_i32 s6, s14, 3

.LBB0_300:
	s_or_b64 exec, exec, s[10:11]
.LBB0_301:
	s_or_b64 exec, exec, s[4:5]
	s_mov_b32 s3, s2
	s_waitcnt lgkmcnt(0)
	s_barrier
	s_cmpk_gt_i32 s3, 0xff
	s_cbranch_scc1 .LBB0_356
	s_mov_b32 s52, 0xbfb8aa3b
	s_mov_b32 s53, 0x800000
	s_mov_b32 s54, 0x3f317217
	s_mov_b32 s55, 0x7f800000
	v_mov_b32_e32 v51, 0x41b17218
	s_movk_i32 s56, 0x410
	v_mov_b32_e32 v49, 0
	s_movk_i32 s57, 0x1600
	s_mov_b64 s[26:27], 0x1000
	s_movk_i32 s58, 0x1000
	s_mov_b64 s[28:29], 0x1800
	s_mov_b64 s[30:31], 0x1100
	s_mov_b64 s[34:35], 0x1900
	s_mov_b64 s[36:37], 0x100
	s_mov_b64 s[38:39], 0x1e40000
	s_mov_b32 s59, 0x1e41000
	s_add_i32 s60, 0, 0x10400
	s_add_i32 s61, 0, 0x14500
	s_add_i32 s62, 0, 0x18600
	s_add_i32 s63, 0, 0x18e00
	s_add_i32 s64, 0, 0x1ae00
	s_add_i32 s65, 0, 0x1b600
	s_movk_i32 s66, 0x208
	s_mov_b32 s67, 0x1e42000
	s_mov_b32 s68, 0x1e43000
	s_mov_b32 s69, 0x2300000
	s_mov_b64 s[40:41], 0x2000
	s_mov_b64 s[42:43], 0x80
	s_mov_b32 s70, 0x1a500
	s_branch .LBB0_304

.LBB0_443:
	s_or_b64 exec, exec, s[10:11]
.LBB0_444:
	s_or_b64 exec, exec, s[4:5]
	s_mov_b64 s[6:7], s[0:1]
	s_mov_b32 s8, s2
	s_waitcnt lgkmcnt(0)
	v_mov_b32_e32 v0, v154
	s_barrier
	s_movk_i32 s3, 0x1000
	v_lshl_add_u32 v2, s8, 9, v0
	s_mov_b32 s10, s33
	v_cmp_gt_i32_e32 vcc, s3, v2
	s_and_saveexec_b64 s[4:5], vcc
	s_cbranch_execz .LBB0_447
	s_load_dwordx2 s[12:13], s[6:7], 0x138
	s_lshl_b32 s3, s10, 9
	v_and_b32_e32 v3, 0x1ff, v0
	v_lshlrev_b32_e32 v0, 5, v0
	v_lshl_add_u32 v4, s8, 14, v0
	s_waitcnt lgkmcnt(0)
	s_add_u32 s6, s12, 0xfc00000
	s_addc_u32 s7, s13, 0
	s_add_u32 s8, s12, 0x80000
	s_addc_u32 s9, s13, 0
	s_lshl_b32 s12, s10, 14
	s_mov_b64 s[10:11], 0
	s_movk_i32 s13, 0xc000
	v_mov_b32_e32 v5, 0
	s_movk_i32 s14, 0xfff

.LBB0_501:
	s_or_b64 exec, exec, s[10:11]
.LBB0_502:
	s_or_b64 exec, exec, s[4:5]
	s_mov_b32 s8, s2
	s_waitcnt lgkmcnt(0)
	s_barrier
	s_cmpk_gt_i32 s8, 0x3ff
	s_cbranch_scc1 .LBB0_523
	s_movk_i32 s3, 0x1600
	s_mov_b32 s11, 0
	s_mov_b64 s[12:13], 0x1000
	s_movk_i32 s15, 0x1000
	s_movk_i32 s17, 0x900
	v_mov_b32_e32 v65, 0
	s_movk_i32 s36, 0x104
	s_mov_b32 s37, 0xbfb8aa3b
	s_mov_b32 s38, 0x800000
	s_mov_b32 s39, 0x3f317217
	s_mov_b32 s40, 0x7f800000
	v_mov_b32_e32 v70, 0x41b17218
	s_mov_b32 s14, 0x3d800000
	s_movk_i32 s41, 0x820
	s_add_i32 s42, 0, 0x18000
	s_mov_b32 s16, 0x3e000000
	s_movk_i32 s43, 0x90
	s_mov_b64 s[18:19], 0xdb00000
	s_movk_i32 s44, 0xff74
	s_movk_i32 s45, 0x214
	s_mov_b64 s[26:27], 0xbb00400
	v_mov_b32_e32 v71, 0x3727c5ac
	s_mov_b32 s46, 0xbb00000
	v_mov_b32_e32 v72, 0x428
	v_mov_b32_e32 v73, 0x63c
	v_mbcnt_hi_u32_b32 v74, -1, v155
	s_branch .LBB0_505

.LBB0_579:
	s_or_b64 exec, exec, s[10:11]
.LBB0_580:
	s_or_b64 exec, exec, s[4:5]
	s_mov_b64 s[4:5], s[0:1]
	s_waitcnt lgkmcnt(0)
	s_barrier
	s_load_dwordx2 s[4:5], s[4:5], 0x138
	s_mov_b32 s3, s33
	s_mov_b32 s38, s2
	v_mov_b32_e32 v8, v154
	s_cmpk_lt_i32 s38, 0x100
	s_cselect_b64 s[6:7], -1, 0
	s_cmpk_gt_i32 s38, 0xff
	v_readfirstlane_b32 s14, v8
	s_cbranch_scc1 .LBB0_586
	s_ashr_i32 s8, s38, 31
	s_lshr_b32 s8, s8, 29
	s_add_i32 s12, s38, s8
	s_and_b32 s8, s12, -8
	s_sub_i32 s10, s38, s8
	s_cmp_gt_i32 s10, -1
	s_cbranch_scc0 .LBB0_583
	s_lshl_b32 s11, s10, 5
	s_ashr_i32 s8, s12, 3
	s_cbranch_execz .LBB0_584
	s_branch .LBB0_585

.LBB0_673:
	s_or_b64 exec, exec, s[10:11]
.LBB0_674:
	s_or_b64 exec, exec, s[4:5]
	s_mov_b32 s100, 0
	s_mov_b64 s[4:5], s[0:1]
	s_mov_b64 s[8:9], s[0:1]
	s_mov_b32 s3, s33
	s_mov_b32 s40, s2
	v_mov_b32_e32 v8, v154
	s_waitcnt lgkmcnt(0)
	s_barrier
	s_cmpk_gt_i32 s40, 0x57f
	v_readfirstlane_b32 s12, v8
	s_cbranch_scc1 .LBB0_690
	v_lshlrev_b32_e32 v0, 4, v8
	v_add_u32_e32 v1, 0x2000, v0
	v_ashrrev_i32_e32 v2, 31, v1
	v_lshrrev_b32_e32 v2, 22, v2
	v_add_u32_e32 v2, v1, v2
	v_ashrrev_i32_e32 v9, 10, v2
	v_mul_i32_i24_e32 v2, 0x400, v9
	v_sub_u32_e32 v1, v1, v2
	v_lshrrev_b32_e32 v2, 4, v1
	v_bitop3_b32 v1, v2, v1, 32 bitop3:0x6c
	v_ashrrev_i32_e32 v2, 31, v1
	v_lshrrev_b32_e32 v2, 26, v2
	v_add_u32_e32 v2, v1, v2
	v_lshlrev_b32_e32 v3, 3, v9
	v_ashrrev_i32_e32 v10, 6, v2
	v_and_b32_e32 v3, -16, v3
	v_add_u32_e32 v3, v10, v3
	s_load_dwordx2 s[10:11], s[8:9], 0x138
	s_load_dwordx2 s[6:7], s[4:5], 0x130
	v_and_b32_e32 v4, 3, v10
	s_mov_b32 s4, 0x1fffe0
	v_lshrrev_b32_e32 v5, 2, v3
	v_lshlrev_b32_e32 v6, 1, v3
	v_and_b32_e32 v2, 0xc0, v2
	v_and_or_b32 v4, v3, s4, v4
	v_and_b32_e32 v5, 4, v5
	v_and_b32_e32 v6, 24, v6
	v_sub_u32_e32 v1, v1, v2
	v_mov_b32_e32 v2, 1
	v_or3_b32 v4, v4, v5, v6
	v_lshlrev_b32_e32 v5, 5, v9
	v_ashrrev_i16_sdwa v1, v2, sext(v1) dst_sel:DWORD dst_unused:UNUSED_PAD src0_sel:DWORD src1_sel:BYTE_0
	v_and_b32_e32 v5, 32, v5
	v_bfe_i32 v11, v1, 0, 16
	v_add_lshl_u32 v1, v5, v11, 1
	v_lshl_add_u32 v128, v4, 11, v1
	v_lshl_add_u32 v130, v3, 11, v1
	v_bfe_i32 v1, v8, 27, 1
	v_lshrrev_b32_e32 v1, 22, v1
	v_add_u32_e32 v1, v0, v1
	v_and_b32_e32 v1, 0xfffffc00, v1
	v_sub_u32_e32 v0, v0, v1
	v_lshrrev_b32_e32 v1, 4, v0
	v_ashrrev_i32_e32 v3, 31, v8
	v_bitop3_b32 v0, v1, v0, 32 bitop3:0x6c
	v_lshrrev_b32_e32 v3, 26, v3
	v_ashrrev_i32_e32 v1, 31, v0
	v_add_u32_e32 v3, v8, v3
	v_lshrrev_b32_e32 v1, 26, v1
	v_ashrrev_i32_e32 v13, 6, v3
	v_add_u32_e32 v1, v0, v1
	v_lshlrev_b32_e32 v3, 3, v13
	s_waitcnt lgkmcnt(0)
	s_add_u32 s41, s10, 0xa80000
	v_ashrrev_i32_e32 v12, 6, v1
	v_and_b32_e32 v3, -16, v3
	s_addc_u32 s42, s11, 0
	v_add_u32_e32 v3, v12, v3
	v_and_b32_e32 v4, 3, v12
	s_ashr_i32 s44, s40, 31
	v_and_or_b32 v4, v3, s4, v4
	s_lshr_b32 s4, s44, 29
	s_add_i32 s4, s40, s4
	s_ashr_i32 s10, s12, 6
	s_ashr_i32 s8, s4, 3
	s_and_b32 s4, s4, -8
	s_ashr_i32 s5, s12, 8
	s_lshl_b32 s43, s10, 10
	s_sub_i32 s4, s40, s4
	s_cmp_lt_i32 s4, 0
	s_movk_i32 s45, 0xb1
	s_cselect_b32 s9, s45, 0xb0
	s_mul_i32 s4, s9, s4
	s_add_i32 s4, s4, s8
	s_mul_hi_i32 s8, s4, 0x2e8ba2e9
	s_lshr_b32 s9, s8, 31
	s_ashr_i32 s8, s8, 5
	s_add_i32 s8, s8, s9
	s_lshl_b32 s9, s8, 3
	s_mulk_i32 s8, 0xb0
	s_sub_i32 s8, s4, s8
	s_bfe_u32 s4, s8, 0x3001c
	s_add_i32 s11, s8, s4
	s_sext_i32_i16 s4, s11
	s_and_b32 s11, s11, 0xfff8
	s_sub_i32 s8, s8, s11
	s_sext_i32_i16 s8, s8
	v_lshrrev_b32_e32 v5, 2, v3
	v_lshlrev_b32_e32 v6, 1, v3
	v_and_b32_e32 v1, 0xc0, v1
	s_lshr_b32 s4, s4, 3
	s_add_i32 s34, s9, s8
	v_and_b32_e32 v5, 4, v5
	v_and_b32_e32 v6, 24, v6
	v_sub_u32_e32 v0, v0, v1
	s_ashr_i32 s35, s34, 31
	s_bfe_i64 s[14:15], s[4:5], 0x100000
	v_or3_b32 v4, v4, v5, v6
	v_lshlrev_b32_e32 v5, 5, v13
	v_ashrrev_i16_sdwa v0, v2, sext(v0) dst_sel:DWORD dst_unused:UNUSED_PAD src0_sel:DWORD src1_sel:BYTE_0
	s_lshl_b64 s[8:9], s[34:35], 19
	s_lshl_b64 s[14:15], s[14:15], 19
	v_and_b32_e32 v5, 32, v5
	v_bfe_i32 v14, v0, 0, 16
	s_add_u32 s30, s41, s14
	v_add_lshl_u32 v0, v5, v14, 1
	s_addc_u32 s31, s42, s15
	s_add_i32 s35, s43, 0
	v_lshl_add_u32 v132, v4, 11, v0
	s_add_i32 m0, s35, 0x10000
	v_lshl_add_u32 v134, v3, 11, v0
	global_load_lds_dwordx4 v132, s[30:31]
	s_add_i32 m0, s35, 0x12000
	s_add_u32 s14, s30, 0x40000
	global_load_lds_dwordx4 v128, s[30:31]
	s_addc_u32 s15, s31, 0
	s_add_i32 m0, s35, 0x14000
	v_mov_b32_e32 v133, 0
	global_load_lds_dwordx4 v132, s[14:15]
	s_add_i32 m0, s35, 0x16000
	s_add_u32 s36, s6, s8
	s_addc_u32 s37, s7, s9
	s_add_i32 s46, s35, 0x2000
	global_load_lds_dwordx4 v128, s[14:15]
	s_mov_b32 m0, s35
	s_add_u32 s8, s36, 0x40000
	global_load_lds_dwordx4 v134, s[36:37]
	s_mov_b32 m0, s46
	s_addc_u32 s9, s37, 0
	s_add_i32 s47, s35, 0x4000
	global_load_lds_dwordx4 v130, s[36:37]
	s_mov_b32 m0, s47
	s_add_i32 s48, s35, 0x6000
	global_load_lds_dwordx4 v134, s[8:9]
	s_mov_b32 m0, s48
	v_mov_b32_e32 v129, v133
	global_load_lds_dwordx4 v130, s[8:9]
	v_mov_b32_e32 v135, v133
	v_mov_b32_e32 v131, v133
	s_cmp_eq_u32 s5, 1
	s_mov_b32 s49, 0
	v_lshl_add_u64 v[6:7], s[30:31], 0, v[132:133]
	v_lshl_add_u64 v[4:5], s[30:31], 0, v[128:129]
	v_lshl_add_u64 v[0:1], s[36:37], 0, v[134:135]
	s_cselect_b64 s[8:9], -1, 0
	s_cmp_lg_u32 s5, 1
	v_lshl_add_u64 v[2:3], s[36:37], 0, v[130:131]
	s_cbranch_scc1 .LBB0_677
	s_barrier

.LBB0_765:
	s_or_b64 exec, exec, s[10:11]
.LBB0_766:
	s_or_b64 exec, exec, s[4:5]
	s_mov_b64 s[4:5], s[0:1]
	s_waitcnt lgkmcnt(0)
	s_barrier
	s_load_dwordx2 s[4:5], s[4:5], 0x138
	s_mov_b32 s3, s33
	s_mov_b32 s30, s2
	v_mov_b32_e32 v8, v154
	s_cmpk_lt_i32 s30, 0x100
	s_cselect_b64 s[6:7], -1, 0
	s_cmpk_gt_i32 s30, 0xff
	v_readfirstlane_b32 s16, v8
	s_cbranch_scc1 .LBB0_772
	s_ashr_i32 s8, s30, 31
	s_lshr_b32 s8, s8, 29
	s_add_i32 s12, s30, s8
	s_and_b32 s8, s12, -8
	s_sub_i32 s10, s30, s8
	s_cmp_gt_i32 s10, -1
	s_cbranch_scc0 .LBB0_769
	s_lshl_b32 s11, s10, 5
	s_ashr_i32 s8, s12, 3
	s_cbranch_execz .LBB0_770
	s_branch .LBB0_771

.LBB0_863:
	s_or_b64 exec, exec, s[10:11]
.LBB0_864:
	s_or_b64 exec, exec, s[4:5]
	s_mov_b64 s[4:5], s[0:1]
	s_mov_b32 s3, s33
	s_mov_b32 s46, s2
	s_waitcnt lgkmcnt(0)
	s_barrier
	v_mov_b32_e32 v8, v154
	s_cmpk_lt_i32 s46, 0x100
	s_cselect_b64 s[6:7], -1, 0
	s_cmpk_gt_i32 s46, 0xff
	v_readfirstlane_b32 s16, v8
	s_cbranch_scc1 .LBB0_870
	s_ashr_i32 s8, s46, 31
	s_lshr_b32 s8, s8, 29
	s_add_i32 s12, s46, s8
	s_and_b32 s8, s12, -8
	s_sub_i32 s10, s46, s8
	s_cmp_gt_i32 s10, -1
	s_cbranch_scc0 .LBB0_867
	s_lshl_b32 s11, s10, 5
	s_ashr_i32 s8, s12, 3
	s_cbranch_execz .LBB0_868
	s_branch .LBB0_869

.LBB0_957:
	s_or_b64 exec, exec, s[10:11]
.LBB0_958:
	s_or_b64 exec, exec, s[4:5]
	s_mov_b32 s100, 0
	s_mov_b64 s[4:5], s[0:1]
	s_mov_b64 s[6:7], s[0:1]
	s_mov_b32 s3, s33
	s_mov_b32 s38, s2
	v_mov_b32_e32 v8, v154
	s_waitcnt lgkmcnt(0)
	s_barrier
	s_cmpk_gt_i32 s38, 0x3bf
	v_readfirstlane_b32 s10, v8
	s_cbranch_scc1 .LBB0_974
	v_lshlrev_b32_e32 v0, 4, v8
	v_add_u32_e32 v1, 0x2000, v0
	v_ashrrev_i32_e32 v2, 31, v1
	v_lshrrev_b32_e32 v2, 22, v2
	v_add_u32_e32 v2, v1, v2
	v_ashrrev_i32_e32 v9, 10, v2
	v_mul_i32_i24_e32 v2, 0x400, v9
	v_sub_u32_e32 v1, v1, v2
	v_lshrrev_b32_e32 v2, 4, v1
	v_bitop3_b32 v1, v2, v1, 32 bitop3:0x6c
	v_ashrrev_i32_e32 v2, 31, v1
	v_lshrrev_b32_e32 v2, 26, v2
	v_add_u32_e32 v2, v1, v2
	v_lshlrev_b32_e32 v3, 3, v9
	v_ashrrev_i32_e32 v10, 6, v2
	v_and_b32_e32 v3, -16, v3
	v_add_u32_e32 v3, v10, v3
	s_load_dwordx2 s[8:9], s[4:5], 0x130
	s_load_dwordx2 s[12:13], s[6:7], 0x138
	v_and_b32_e32 v4, 3, v10
	s_mov_b32 s4, 0x1fffe0
	v_lshrrev_b32_e32 v5, 2, v3
	v_lshlrev_b32_e32 v6, 1, v3
	v_and_b32_e32 v2, 0xc0, v2
	v_and_or_b32 v4, v3, s4, v4
	v_and_b32_e32 v5, 4, v5
	v_and_b32_e32 v6, 24, v6
	v_sub_u32_e32 v1, v1, v2
	v_mov_b32_e32 v2, 1
	v_or3_b32 v4, v4, v5, v6
	v_lshlrev_b32_e32 v5, 5, v9
	v_ashrrev_i16_sdwa v1, v2, sext(v1) dst_sel:DWORD dst_unused:UNUSED_PAD src0_sel:DWORD src1_sel:BYTE_0
	v_and_b32_e32 v5, 32, v5
	v_bfe_i32 v11, v1, 0, 16
	v_add_lshl_u32 v1, v5, v11, 1
	v_lshl_add_u32 v128, v4, 11, v1
	v_lshl_add_u32 v130, v3, 11, v1
	v_bfe_i32 v1, v8, 27, 1
	v_lshrrev_b32_e32 v1, 22, v1
	v_add_u32_e32 v1, v0, v1
	v_and_b32_e32 v1, 0xfffffc00, v1
	v_sub_u32_e32 v0, v0, v1
	v_lshrrev_b32_e32 v1, 4, v0
	v_ashrrev_i32_e32 v3, 31, v8
	v_bitop3_b32 v0, v1, v0, 32 bitop3:0x6c
	v_lshrrev_b32_e32 v3, 26, v3
	v_ashrrev_i32_e32 v1, 31, v0
	v_add_u32_e32 v3, v8, v3
	s_waitcnt lgkmcnt(0)
	s_add_u32 s39, s8, 0x2000000
	v_lshrrev_b32_e32 v1, 26, v1
	v_ashrrev_i32_e32 v13, 6, v3
	s_addc_u32 s40, s9, 0
	v_add_u32_e32 v1, v0, v1
	v_lshlrev_b32_e32 v3, 3, v13
	s_add_u32 s41, s12, 0x100000
	v_ashrrev_i32_e32 v12, 6, v1
	v_and_b32_e32 v3, -16, v3
	s_addc_u32 s42, s13, 0
	v_add_u32_e32 v3, v12, v3
	v_and_b32_e32 v4, 3, v12
	s_ashr_i32 s44, s38, 31
	v_and_or_b32 v4, v3, s4, v4
	s_lshr_b32 s4, s44, 29
	s_add_i32 s4, s38, s4
	s_ashr_i32 s5, s10, 6
	s_ashr_i32 s6, s4, 3
	s_and_b32 s4, s4, -8
	s_ashr_i32 s8, s10, 8
	s_lshl_b32 s43, s5, 10
	s_sub_i32 s4, s38, s4
	s_cmp_lt_i32 s4, 0
	s_movk_i32 s45, 0x79
	s_cselect_b32 s7, s45, 0x78
	s_mul_i32 s4, s7, s4
	s_add_i32 s4, s4, s6
	s_mul_hi_i32 s6, s4, 0x88888889
	s_add_i32 s6, s6, s4
	s_lshr_b32 s7, s6, 31
	s_ashr_i32 s6, s6, 6
	s_add_i32 s6, s6, s7
	s_lshl_b32 s7, s6, 3
	s_mulk_i32 s6, 0x78
	s_sub_i32 s6, s4, s6
	s_bfe_i32 s4, s6, 0x80000
	s_bfe_u32 s4, s4, 0x3000c
	s_add_i32 s9, s6, s4
	s_bfe_i32 s4, s9, 0x80000
	s_and_b32 s9, s9, 0xf8
	s_sub_i32 s6, s6, s9
	s_sext_i32_i16 s4, s4
	s_sext_i32_i8 s6, s6
	v_lshrrev_b32_e32 v5, 2, v3
	v_lshlrev_b32_e32 v6, 1, v3
	v_and_b32_e32 v1, 0xc0, v1
	s_lshr_b32 s4, s4, 3
	s_add_i32 s28, s7, s6
	v_and_b32_e32 v5, 4, v5
	v_and_b32_e32 v6, 24, v6
	v_sub_u32_e32 v0, v0, v1
	s_ashr_i32 s29, s28, 31
	s_bfe_i64 s[12:13], s[4:5], 0x100000
	v_or3_b32 v4, v4, v5, v6
	v_lshlrev_b32_e32 v5, 5, v13
	v_ashrrev_i16_sdwa v0, v2, sext(v0) dst_sel:DWORD dst_unused:UNUSED_PAD src0_sel:DWORD src1_sel:BYTE_0
	s_lshl_b64 s[6:7], s[28:29], 19
	s_lshl_b64 s[12:13], s[12:13], 19
	v_and_b32_e32 v5, 32, v5
	v_bfe_i32 v14, v0, 0, 16
	s_add_u32 s30, s41, s12
	v_add_lshl_u32 v0, v5, v14, 1
	s_addc_u32 s31, s42, s13
	s_add_i32 s46, s43, 0
	v_lshl_add_u32 v132, v4, 11, v0
	s_add_i32 m0, s46, 0x10000
	v_lshl_add_u32 v134, v3, 11, v0
	global_load_lds_dwordx4 v132, s[30:31]
	s_add_i32 m0, s46, 0x12000
	s_add_u32 s12, s30, 0x40000
	global_load_lds_dwordx4 v128, s[30:31]
	s_addc_u32 s13, s31, 0
	s_add_i32 m0, s46, 0x14000
	v_mov_b32_e32 v133, 0
	global_load_lds_dwordx4 v132, s[12:13]
	s_add_i32 m0, s46, 0x16000
	s_add_u32 s34, s39, s6
	s_addc_u32 s35, s40, s7
	s_add_i32 s47, s46, 0x2000
	global_load_lds_dwordx4 v128, s[12:13]
	s_mov_b32 m0, s46
	s_add_u32 s6, s34, 0x40000
	global_load_lds_dwordx4 v134, s[34:35]
	s_mov_b32 m0, s47
	s_addc_u32 s7, s35, 0
	s_add_i32 s48, s46, 0x4000
	global_load_lds_dwordx4 v130, s[34:35]
	s_mov_b32 m0, s48
	s_add_i32 s49, s46, 0x6000
	global_load_lds_dwordx4 v134, s[6:7]
	s_mov_b32 m0, s49
	v_mov_b32_e32 v129, v133
	global_load_lds_dwordx4 v130, s[6:7]
	v_mov_b32_e32 v135, v133
	v_mov_b32_e32 v131, v133
	s_cmp_eq_u32 s8, 1
	s_mov_b32 s50, 0
	v_lshl_add_u64 v[6:7], s[30:31], 0, v[132:133]
	v_lshl_add_u64 v[4:5], s[30:31], 0, v[128:129]
	v_lshl_add_u64 v[0:1], s[34:35], 0, v[134:135]
	s_cselect_b64 s[6:7], -1, 0
	s_cmp_lg_u32 s8, 1
	v_lshl_add_u64 v[2:3], s[34:35], 0, v[130:131]
	s_cbranch_scc1 .LBB0_961
	s_barrier

.LBB0_1025:
	s_or_b64 exec, exec, s[10:11]
.LBB0_1026:
	s_or_b64 exec, exec, s[4:5]
	s_mov_b32 s4, s2
	s_waitcnt lgkmcnt(0)
	s_barrier
	s_cmpk_gt_i32 s4, 0x1ff
	s_cbranch_scc1 .LBB0_1029
	s_movk_i32 s3, 0x1e00
	s_mov_b32 s7, 0
	s_add_i32 s14, 0, 0x11000
	s_movk_i32 s15, 0x2200
	s_mov_b32 s16, 0xc2fc0000
	v_mov_b32_e32 v4, 0x42800000
	s_mov_b32 s17, 0x3f2aaaab
	v_mov_b32_e32 v5, 0x3ecc95a3
	s_mov_b32 s18, 0x3f317218
	v_mov_b32_e32 v6, 0x7fc00000
	v_mov_b32_e32 v7, 0xff800000
	s_mov_b32 s19, 0x33800000
	v_mov_b32_e32 v1, 0

.LBB0_1117:
	s_or_b64 exec, exec, s[10:11]
.LBB0_1118:
	s_or_b64 exec, exec, s[4:5]
	s_mov_b64 s[4:5], s[0:1]
	s_mov_b32 s3, s2
	s_waitcnt lgkmcnt(0)
	v_mov_b32_e32 v0, v154
	s_barrier
	s_mov_b32 s6, 0x40000
	v_lshl_add_u32 v2, s3, 9, v0
	s_mov_b32 s3, s33
	v_cmp_gt_i32_e32 vcc, s6, v2
	s_and_saveexec_b64 s[6:7], vcc
	s_cbranch_execz .LBB0_1121
	s_load_dwordx2 s[4:5], s[4:5], 0x138
	s_lshl_b32 s3, s3, 9
	s_mov_b64 s[8:9], 0
	s_mov_b32 s12, 0xc2fc0000
	v_mov_b32_e32 v3, 0
	s_waitcnt lgkmcnt(0)
	s_add_u32 s10, s4, 0x2300000
	s_addc_u32 s11, s5, 0
	v_mov_b32_e32 v4, 0x42800000
	v_not_b32_e32 v5, 63
	s_mov_b32 s13, 0x3f2aaaab
	v_mov_b32_e32 v6, 0x3ecc95a3
	s_mov_b32 s14, 0x3f317218
	v_mov_b32_e32 v7, 0x7fc00000
	v_mov_b32_e32 v8, 0xff800000
	s_mov_b32 s15, 0x33800000
	s_mov_b32 s16, 0x3ffff
	v_mov_b32_e32 v0, 0x3f317218

.LBB0_1226:
	s_or_b64 exec, exec, s[10:11]
.LBB0_1227:
	s_or_b64 exec, exec, s[4:5]
	s_mov_b32 s4, s2
	s_waitcnt lgkmcnt(0)
	s_barrier
	s_cmpk_gt_i32 s4, 0x1ff
	s_cbranch_scc1 .LBB0_1246
	s_movk_i32 s3, 0x1e00
	s_mov_b32 s7, 0
	s_add_i32 s11, 0, 0x11000
	s_movk_i32 s26, 0x2200
	s_mov_b32 s27, 0xc2fc0000
	v_mov_b32_e32 v106, 0x42800000
	s_mov_b32 s28, 0x3f2aaaab
	v_mov_b32_e32 v107, 0x3ecc95a3
	s_mov_b32 s29, 0x3f317218
	v_mov_b32_e32 v108, 0x7fc00000
	v_mov_b32_e32 v109, 0xff800000
	s_mov_b32 s30, 0x33800000
	v_mov_b32_e32 v69, 0
	s_movk_i32 s31, 0x110
	s_add_i32 s34, 0, 0x19800
	s_mov_b64 s[8:9], 0x2300000
	s_mov_b32 s35, 0x2301000
	s_mov_b32 s36, 0x2302000
	s_mov_b32 s37, 0x2303000
	s_mov_b32 s38, 0x2304000
	s_mov_b32 s39, 0x2305000
	s_mov_b32 s40, 0x2306000
	s_mov_b32 s41, 0x2307000
	s_movk_i32 s42, 0x214
	s_brev_b32 s10, 60
	v_mov_b32_e32 v70, 0x3f317218
	v_mbcnt_hi_u32_b32 v110, -1, v155
	s_branch .LBB0_1230

.LBB0_1450:
	s_or_b64 exec, exec, s[10:11]
.LBB0_1451:
	s_or_b64 exec, exec, s[4:5]
	s_mov_b64 s[10:11], s[0:1]
	s_mov_b32 s18, s2
	s_waitcnt vmcnt(7) lgkmcnt(0)
	v_mov_b32_e32 v0, v154
	s_barrier
	s_mov_b32 s3, 0x100000
	v_lshl_add_u32 v28, s18, 9, v0
	s_mov_b32 s19, s33
	v_cmp_gt_i32_e32 vcc, s3, v28
	s_and_saveexec_b64 s[4:5], vcc
	s_cbranch_execz .LBB0_1456
	v_mbcnt_hi_u32_b32 v1, -1, v155
	s_load_dwordx2 s[6:7], s[10:11], 0x138
	v_and_b32_e32 v3, 64, v1
	v_xor_b32_e32 v2, 1, v1
	v_add_u32_e32 v3, 64, v3
	v_cmp_lt_i32_e32 vcc, v2, v3
	s_lshl_b32 s3, s19, 9
	s_load_dwordx2 s[16:17], s[10:11], 0x88
	s_load_dwordx2 s[8:9], s[10:11], 0xd0
	v_cndmask_b32_e32 v2, v1, v2, vcc
	v_lshlrev_b32_e32 v29, 2, v2
	v_xor_b32_e32 v2, 2, v1
	s_waitcnt lgkmcnt(0)
	s_add_u32 s10, s6, 0x4300000
	v_cmp_lt_i32_e32 vcc, v2, v3
	s_addc_u32 s11, s7, 0
	s_add_u32 s12, s6, 0x3300000
	v_cndmask_b32_e32 v2, v1, v2, vcc
	v_lshlrev_b32_e32 v30, 2, v2
	v_xor_b32_e32 v2, 4, v1
	s_addc_u32 s13, s7, 0
	v_cmp_lt_i32_e32 vcc, v2, v3
	s_add_u32 s14, s6, 0xfb00000
	s_addc_u32 s15, s7, 0
	v_cndmask_b32_e32 v1, v1, v2, vcc
	v_lshlrev_b32_e32 v31, 2, v1
	v_and_b32_e32 v1, 7, v0
	s_add_u32 s16, s16, 0x1000
	s_waitcnt vmcnt(0)
	v_lshlrev_b32_e32 v32, 3, v1
	v_lshlrev_b32_e32 v1, 10, v0
	v_lshlrev_b32_e32 v0, 3, v0
	s_addc_u32 s17, s17, 0
	v_and_b32_e32 v33, 0x1800, v1
	v_lshl_add_u32 v34, s18, 12, v0
	s_lshl_b32 s28, s19, 12
	s_mov_b64 s[18:19], 0
	v_mov_b32_e32 v5, 0
	s_movk_i32 s29, 0x1e00
	v_mov_b64_e32 v[6:7], s[10:11]
	v_mov_b32_e32 v35, 0x3a27c5ac
	s_movk_i32 s30, 0xc00
	s_mov_b32 s31, 0xbb00000
	s_mov_b32 s34, 0xfffff
	s_branch .LBB0_1454

.LBB0_1507:
	s_or_b64 exec, exec, s[10:11]
.LBB0_1508:
	s_or_b64 exec, exec, s[4:5]
	s_mov_b64 s[4:5], s[0:1]
	s_waitcnt lgkmcnt(0)
	s_barrier
	s_load_dwordx2 s[4:5], s[4:5], 0x138
	s_mov_b32 s3, s33
	s_mov_b32 s36, s2
	s_waitcnt vmcnt(2)
	v_mov_b32_e32 v8, v154
	s_cmpk_lt_i32 s36, 0x100
	s_cselect_b64 s[6:7], -1, 0
	s_cmpk_gt_i32 s36, 0xff
	v_readfirstlane_b32 s16, v8
	s_cbranch_scc1 .LBB0_1514
	s_ashr_i32 s8, s36, 31
	s_lshr_b32 s8, s8, 29
	s_add_i32 s12, s36, s8
	s_and_b32 s8, s12, -8
	s_sub_i32 s10, s36, s8
	s_cmp_gt_i32 s10, -1
	s_cbranch_scc0 .LBB0_1511
	s_lshl_b32 s11, s10, 5
	s_ashr_i32 s8, s12, 3
	s_cbranch_execz .LBB0_1512
	s_branch .LBB0_1513

.LBB0_1603:
	s_or_b64 exec, exec, s[10:11]
.LBB0_1604:
	s_or_b64 exec, exec, s[4:5]
	s_mov_b32 s100, 0
	s_mov_b64 s[4:5], s[0:1]
	s_mov_b64 s[6:7], s[0:1]
	s_mov_b32 s3, s33
	s_mov_b32 s38, s2
	v_mov_b32_e32 v8, v154
	s_waitcnt lgkmcnt(0)
	s_barrier
	s_cmpk_gt_i32 s38, 0x57f
	v_readfirstlane_b32 s10, v8
	s_cbranch_scc1 .LBB0_1620
	v_lshlrev_b32_e32 v0, 4, v8
	v_add_u32_e32 v1, 0x2000, v0
	v_ashrrev_i32_e32 v2, 31, v1
	v_lshrrev_b32_e32 v2, 22, v2
	v_add_u32_e32 v2, v1, v2
	v_ashrrev_i32_e32 v9, 10, v2
	v_mul_i32_i24_e32 v2, 0x400, v9
	v_sub_u32_e32 v1, v1, v2
	v_lshrrev_b32_e32 v2, 4, v1
	v_bitop3_b32 v1, v2, v1, 32 bitop3:0x6c
	v_ashrrev_i32_e32 v2, 31, v1
	v_lshrrev_b32_e32 v2, 26, v2
	v_add_u32_e32 v2, v1, v2
	v_lshlrev_b32_e32 v3, 3, v9
	v_ashrrev_i32_e32 v10, 6, v2
	v_and_b32_e32 v3, -16, v3
	v_add_u32_e32 v3, v10, v3
	s_load_dwordx2 s[8:9], s[4:5], 0x130
	s_load_dwordx2 s[12:13], s[6:7], 0x138
	v_and_b32_e32 v4, 3, v10
	s_mov_b32 s4, 0x1fffe0
	v_lshrrev_b32_e32 v5, 2, v3
	v_lshlrev_b32_e32 v6, 1, v3
	v_and_b32_e32 v2, 0xc0, v2
	v_and_or_b32 v4, v3, s4, v4
	v_and_b32_e32 v5, 4, v5
	v_and_b32_e32 v6, 24, v6
	v_sub_u32_e32 v1, v1, v2
	v_mov_b32_e32 v2, 1
	v_or3_b32 v4, v4, v5, v6
	v_lshlrev_b32_e32 v5, 5, v9
	v_ashrrev_i16_sdwa v1, v2, sext(v1) dst_sel:DWORD dst_unused:UNUSED_PAD src0_sel:DWORD src1_sel:BYTE_0
	v_and_b32_e32 v5, 32, v5
	v_bfe_i32 v11, v1, 0, 16
	v_add_lshl_u32 v1, v5, v11, 1
	v_lshl_add_u32 v128, v4, 11, v1
	v_lshl_add_u32 v130, v3, 11, v1
	v_bfe_i32 v1, v8, 27, 1
	v_lshrrev_b32_e32 v1, 22, v1
	v_add_u32_e32 v1, v0, v1
	v_and_b32_e32 v1, 0xfffffc00, v1
	v_sub_u32_e32 v0, v0, v1
	v_lshrrev_b32_e32 v1, 4, v0
	v_ashrrev_i32_e32 v3, 31, v8
	v_bitop3_b32 v0, v1, v0, 32 bitop3:0x6c
	v_lshrrev_b32_e32 v3, 26, v3
	v_ashrrev_i32_e32 v1, 31, v0
	v_add_u32_e32 v3, v8, v3
	s_waitcnt lgkmcnt(0)
	s_add_u32 s39, s8, 0x2000000
	v_lshrrev_b32_e32 v1, 26, v1
	v_ashrrev_i32_e32 v13, 6, v3
	s_addc_u32 s40, s9, 0
	v_add_u32_e32 v1, v0, v1
	v_lshlrev_b32_e32 v3, 3, v13
	s_add_u32 s41, s12, 0xa80000
	v_ashrrev_i32_e32 v12, 6, v1
	v_and_b32_e32 v3, -16, v3
	s_addc_u32 s42, s13, 0
	v_add_u32_e32 v3, v12, v3
	v_and_b32_e32 v4, 3, v12
	s_ashr_i32 s44, s38, 31
	v_and_or_b32 v4, v3, s4, v4
	s_lshr_b32 s4, s44, 29
	s_add_i32 s4, s38, s4
	s_ashr_i32 s8, s10, 6
	s_ashr_i32 s6, s4, 3
	s_and_b32 s4, s4, -8
	s_ashr_i32 s5, s10, 8
	s_lshl_b32 s43, s8, 10
	s_sub_i32 s4, s38, s4
	s_cmp_lt_i32 s4, 0
	s_movk_i32 s45, 0xb1
	s_cselect_b32 s7, s45, 0xb0
	s_mul_i32 s4, s7, s4
	s_add_i32 s4, s4, s6
	s_mul_hi_i32 s6, s4, 0x2e8ba2e9
	s_lshr_b32 s7, s6, 31
	s_ashr_i32 s6, s6, 5
	s_add_i32 s6, s6, s7
	s_lshl_b32 s7, s6, 3
	s_mulk_i32 s6, 0xb0
	s_sub_i32 s6, s4, s6
	s_bfe_u32 s4, s6, 0x3001c
	s_add_i32 s9, s6, s4
	s_sext_i32_i16 s4, s9
	s_and_b32 s9, s9, 0xfff8
	s_sub_i32 s6, s6, s9
	s_sext_i32_i16 s6, s6
	v_lshrrev_b32_e32 v5, 2, v3
	v_lshlrev_b32_e32 v6, 1, v3
	v_and_b32_e32 v1, 0xc0, v1
	s_lshr_b32 s4, s4, 3
	s_add_i32 s30, s7, s6
	v_and_b32_e32 v5, 4, v5
	v_and_b32_e32 v6, 24, v6
	v_sub_u32_e32 v0, v0, v1
	s_ashr_i32 s31, s30, 31
	s_bfe_i64 s[12:13], s[4:5], 0x100000
	v_or3_b32 v4, v4, v5, v6
	v_lshlrev_b32_e32 v5, 5, v13
	v_ashrrev_i16_sdwa v0, v2, sext(v0) dst_sel:DWORD dst_unused:UNUSED_PAD src0_sel:DWORD src1_sel:BYTE_0
	s_lshl_b64 s[6:7], s[30:31], 19
	s_lshl_b64 s[12:13], s[12:13], 19
	v_and_b32_e32 v5, 32, v5
	v_bfe_i32 v14, v0, 0, 16
	s_add_u32 s28, s41, s12
	v_add_lshl_u32 v0, v5, v14, 1
	s_addc_u32 s29, s42, s13
	s_add_i32 s31, s43, 0
	v_lshl_add_u32 v132, v4, 11, v0
	s_add_i32 m0, s31, 0x10000
	v_lshl_add_u32 v134, v3, 11, v0
	global_load_lds_dwordx4 v132, s[28:29]
	s_add_i32 m0, s31, 0x12000
	s_add_u32 s12, s28, 0x40000
	global_load_lds_dwordx4 v128, s[28:29]
	s_addc_u32 s13, s29, 0
	s_add_i32 m0, s31, 0x14000
	v_mov_b32_e32 v133, 0
	global_load_lds_dwordx4 v132, s[12:13]
	s_add_i32 m0, s31, 0x16000
	s_add_u32 s34, s39, s6
	s_addc_u32 s35, s40, s7
	s_add_i32 s46, s31, 0x2000
	global_load_lds_dwordx4 v128, s[12:13]
	s_mov_b32 m0, s31
	s_add_u32 s6, s34, 0x40000
	global_load_lds_dwordx4 v134, s[34:35]
	s_mov_b32 m0, s46
	s_addc_u32 s7, s35, 0
	s_add_i32 s47, s31, 0x4000
	global_load_lds_dwordx4 v130, s[34:35]
	s_mov_b32 m0, s47
	s_add_i32 s48, s31, 0x6000
	global_load_lds_dwordx4 v134, s[6:7]
	s_mov_b32 m0, s48
	v_mov_b32_e32 v129, v133
	global_load_lds_dwordx4 v130, s[6:7]
	v_mov_b32_e32 v135, v133
	v_mov_b32_e32 v131, v133
	s_cmp_eq_u32 s5, 1
	s_mov_b32 s49, 0
	v_lshl_add_u64 v[6:7], s[28:29], 0, v[132:133]
	v_lshl_add_u64 v[4:5], s[28:29], 0, v[128:129]
	v_lshl_add_u64 v[0:1], s[34:35], 0, v[134:135]
	s_cselect_b64 s[6:7], -1, 0
	s_cmp_lg_u32 s5, 1
	v_lshl_add_u64 v[2:3], s[34:35], 0, v[130:131]
	s_cbranch_scc1 .LBB0_1607
	s_barrier

.LBB0_1695:
	s_or_b64 exec, exec, s[10:11]
.LBB0_1696:
	s_or_b64 exec, exec, s[4:5]
	s_mov_b64 s[4:5], s[0:1]
	s_waitcnt lgkmcnt(0)
	s_barrier
	s_load_dwordx2 s[4:5], s[4:5], 0x138
	s_mov_b32 s3, s33
	s_mov_b32 s30, s2
	v_mov_b32_e32 v8, v154
	s_cmpk_lt_i32 s30, 0x100
	s_cselect_b64 s[6:7], -1, 0
	s_cmpk_gt_i32 s30, 0xff
	v_readfirstlane_b32 s16, v8
	s_cbranch_scc1 .LBB0_1702
	s_ashr_i32 s8, s30, 31
	s_lshr_b32 s8, s8, 29
	s_add_i32 s12, s30, s8
	s_and_b32 s8, s12, -8
	s_sub_i32 s10, s30, s8
	s_cmp_gt_i32 s10, -1
	s_cbranch_scc0 .LBB0_1699
	s_lshl_b32 s11, s10, 5
	s_ashr_i32 s8, s12, 3
	s_cbranch_execz .LBB0_1700
	s_branch .LBB0_1701

.LBB0_1793:
	s_or_b64 exec, exec, s[10:11]
.LBB0_1794:
	s_or_b64 exec, exec, s[4:5]
	s_mov_b64 s[8:9], s[0:1]
	s_mov_b32 s3, s33
	s_mov_b32 s44, s2
	s_waitcnt lgkmcnt(0)
	s_barrier
	v_mov_b32_e32 v8, v154
	s_cmpk_lt_i32 s44, 0x100
	s_cselect_b64 s[10:11], -1, 0
	s_cmpk_gt_i32 s44, 0xff
	v_readfirstlane_b32 s14, v8
	s_cbranch_scc1 .LBB0_1800
	s_ashr_i32 s4, s44, 31
	s_lshr_b32 s4, s4, 29
	s_add_i32 s12, s44, s4
	s_and_b32 s4, s12, -8
	s_sub_i32 s6, s44, s4
	s_cmp_gt_i32 s6, -1
	s_cbranch_scc0 .LBB0_1797
	s_lshl_b32 s7, s6, 5
	s_ashr_i32 s4, s12, 3
	s_cbranch_execz .LBB0_1798
	s_branch .LBB0_1799

.LBB0_1887:
	s_or_b64 exec, exec, s[10:11]
.LBB0_1888:
	s_or_b64 exec, exec, s[4:5]
	s_waitcnt lgkmcnt(0)
	v_mov_b32_e32 v0, v154
	s_barrier
	s_lshl_b32 s2, s2, 3
	v_readfirstlane_b32 s3, v0
	s_ashr_i32 s3, s3, 6
	s_add_i32 s2, s3, s2
	s_cmpk_gt_i32 s2, 0x3fff
	s_cbranch_scc1 .LBB0_1893
	s_load_dwordx4 s[4:7], s[0:1], 0x128
	s_load_dwordx2 s[10:11], s[0:1], 0x138
	s_ashr_i32 s3, s2, 31
	s_lshl_b32 s8, s33, 3
	s_lshl_b64 s[0:1], s[2:3], 6
	v_mov_b32_e32 v38, 0xfe00000
	s_waitcnt lgkmcnt(0)
	s_add_u32 s0, s10, s0
	s_addc_u32 s1, s11, s1
	s_add_u32 s12, s0, 0xfe00000
	v_and_b32_e32 v18, 63, v154
	v_mov_b32_e32 v17, 0
	s_addc_u32 s13, s1, 0
	global_load_dwordx4 v[30:33], v38, s[0:1]
	global_load_dwordx4 v[34:37], v17, s[12:13] offset:16
	global_load_dwordx4 v[40:43], v17, s[12:13] offset:32
	v_lshlrev_b32_e32 v16, 4, v18
	global_load_dwordx4 v[0:3], v16, s[4:5]
	global_load_dwordx4 v[4:7], v16, s[4:5] offset:1024
	global_load_dwordx4 v[44:47], v17, s[12:13] offset:48
	global_load_dwordx4 v[8:11], v16, s[4:5] offset:2048
	global_load_dwordx4 v[12:15], v16, s[4:5] offset:3072
	s_lshl_b64 s[0:1], s[2:3], 11
	s_add_u32 s0, s10, s0
	s_addc_u32 s1, s11, s1
	v_lshlrev_b32_e32 v24, 3, v18
	v_mov_b32_e32 v25, v17
	v_lshl_add_u64 v[18:19], s[0:1], 0, v[24:25]
	s_mov_b64 s[0:1], 0x6b00000
	s_mov_b32 s16, 0x6b00000
	v_lshl_add_u64 v[20:21], v[18:19], 0, s[0:1]
	v_add_co_u32_e32 v48, vcc, s16, v18
	s_add_i32 s14, s2, s8
	s_nop 0
	v_addc_co_u32_e32 v49, vcc, 0, v19, vcc
	global_load_dwordx2 v[26:27], v[20:21], off offset:512
	global_load_dwordx2 v[28:29], v[48:49], off
	global_load_dwordx2 v[22:23], v[20:21], off offset:1024
	global_load_dwordx2 v[18:19], v[20:21], off offset:1536
	s_ashr_i32 s9, s8, 31
	s_ashr_i32 s15, s14, 31
	s_lshl_b64 s[18:19], s[2:3], 12
	s_lshl_b64 s[0:1], s[8:9], 6
	s_lshl_b64 s[4:5], s[14:15], 6
	s_add_u32 s18, s6, s18
	s_addc_u32 s19, s7, s19
	v_mov_b32_e32 v39, 0x358637bd
	v_lshl_add_u64 v[20:21], s[18:19], 0, v[16:17]
	s_mov_b64 s[12:13], 0x800
	v_lshl_add_u64 v[20:21], v[20:21], 0, s[12:13]
	s_lshl_b64 s[12:13], s[14:15], 11
	s_lshl_b64 s[6:7], s[8:9], 12
	v_or_b32_e32 v24, s12, v24
	v_mov_b32_e32 v25, s13
	s_lshl_b64 s[12:13], s[8:9], 11
	s_waitcnt vmcnt(11)
	v_mov_b32_e32 v48, v30
	v_mov_b32_e32 v30, v32
	s_waitcnt vmcnt(9)
	v_mov_b32_e32 v49, v40
	v_mov_b32_e32 v40, v31
	v_mov_b32_e32 v31, v42
	v_mov_b32_e32 v42, v33
	v_mov_b32_e32 v32, v34
	s_waitcnt vmcnt(6)
	v_mov_b32_e32 v33, v44
	v_mov_b32_e32 v44, v35
	v_mov_b32_e32 v34, v36
	v_mov_b32_e32 v35, v46
	v_mov_b32_e32 v46, v37
	v_pk_add_f32 v[36:37], v[48:49], v[40:41]
	v_pk_add_f32 v[30:31], v[30:31], v[42:43]
	v_pk_add_f32 v[32:33], v[32:33], v[44:45]
	v_pk_add_f32 v[34:35], v[34:35], v[46:47]
	v_pk_add_f32 v[30:31], v[36:37], v[30:31]
	v_pk_add_f32 v[32:33], v[32:33], v[34:35]
	s_nop 0
	v_pk_add_f32 v[30:31], v[30:31], v[32:33]
	s_nop 0
	v_add_f32_e32 v16, v30, v31
	v_fmamk_f32 v16, v16, 0x3a800000, v39
	v_rsq_f32_e32 v16, v16
	s_branch .LBB0_1891
